# attention: query loads issued at the item top after the key rope loads; top wait is vmcnt(8) (K/V + rope), Q stays in flight across rope math, LDS writes and barrier
# speedup vs baseline: 1.0057x; 1.0057x over previous
; #define LAS __attribute__((address_space(3)))
; __device__ __forceinline__ void p4_attn(const Params& p, LAS unsigned char* lds, const int dummy) {
;     ...
;         {
;             const int row = tid >> 1, pv = tid & 1; const int jk = blk * 128 - 128 + row;
;             u32x4 o1 = kr[0], o2 = kr[1];
;             if (jk >= 0) {
;                 const int pos = jk * dil + rr;
;                 float x1[8], x2[8]; unpack8(kr[0], x1); unpack8(kr[1], x2);
;                 const float4 ca = *(const float4*)(RC + pos * 16 + 8 * pv), cb = *(const float4*)(RC + pos * 16 + 8 * pv + 4);
;                 const float4 sa = *(const float4*)(RS + pos * 16 + 8 * pv), sb = *(const float4*)(RS + pos * 16 + 8 * pv + 4);
;                 const float cc[8] = {ca.x, ca.y, ca.z, ca.w, cb.x, cb.y, cb.z, cb.w}, sn[8] = {sa.x, sa.y, sa.z, sa.w, sb.x, sb.y, sb.z, sb.w};
;                 float y1[8], y2[8];
; #pragma unroll
;                 for (int e = 0; e < 8; ++e) { y1[e] = x1[e] * cc[e] - x2[e] * sn[e]; y2[e] = x2[e] * cc[e] + x1[e] * sn[e]; }
;                 o1 = pack8(y1); o2 = pack8(y2);
;             }
;             *(LAS u32x4*)(KA + row * KA_STRIDE + (8 * pv) * 2) = o1;
;             *(LAS u32x4*)(KA + row * KA_STRIDE + (16 + 8 * pv) * 2) = o2;
; #pragma unroll
;             for (int i = 0; i < 6; ++i) { const int task = tid + 512 * i; const int row2 = task / 12, v = 4 + task % 12; *(LAS u32x4*)(KA + row2 * KA_STRIDE + v * 16) = kr[2 + i]; }
; #pragma unroll
;             for (int vi = 0; vi < 8; ++vi) *(LAS u32x4*)(VB + row * VB_STRIDE + (pv * 64 + vi * 8) * 2) = vr[vi];
;         }
;         const int ql = 16 * wid + r; const int jq = blk * 128 + ql; const int posq = jq * dil + rr; const size_t tq = (size_t)(tokb + posq);
;         bf16x8 qf[4];
;         {
;             bf16_t* qsrc = R1 + tq * QZ_LD + qcol;
; #pragma unroll
;             for (int kk = 0; kk < 4; ++kk) {
;                 const u32x4 av = *(const u32x4*)(qsrc + 32 * kk + 8 * q);
;                 float x[8]; unpack8(av, x);
;                 if (kk == 0) {
;                     const int fi = 8 * (q & 1);
;                     const float4 ca = *(const float4*)(RC + posq * 16 + fi), cb = *(const float4*)(RC + posq * 16 + fi + 4);
;                     const float4 sa = *(const float4*)(RS + posq * 16 + fi), sb = *(const float4*)(RS + posq * 16 + fi + 4);
.LBB0_592:
	s_ashr_i32 s1, s8, 6
	s_mul_hi_i32 s4, s1, 0x55555556
	s_lshr_b32 s5, s4, 31
	s_add_i32 s4, s4, s5
	s_mul_i32 s4, s4, 3
	s_sub_i32 s9, s1, s4
	s_lshl_b32 s4, s9, 1
	s_lshr_b32 s1, 16, s4
	s_and_b32 s0, s8, 15
	s_add_i32 s1, s1, -1
	s_and_b32 s81, s1, s0
	s_lshl_b32 s11, s81, 7
	s_sub_i32 s1, 4, s4
	s_lshr_b32 s5, s0, s1
	v_add_u32_e32 v37, s11, v144
	v_cmp_lt_i32_e32 vcc, -1, v37
	s_and_saveexec_b64 s[0:1], vcc
	s_cbranch_execz .Lat_norope
	v_lshlrev_b32_e32 v37, s4, v37
	v_add_lshl_u32 v38, v37, s5, 4
	v_mov_b32_e32 v39, v36
	v_lshlrev_b64 v[38:39], 2, v[38:39]
	v_lshl_add_u64 v[218:219], v[112:113], 0, v[38:39]
	v_lshl_add_u64 v[38:39], v[114:115], 0, v[38:39]
	global_load_dwordx4 v[214:217], v[218:219], off offset:16
	s_nop 0
	global_load_dwordx4 v[218:221], v[218:219], off
	s_nop 0
	global_load_dwordx4 v[222:225], v[38:39], off offset:16
	global_load_dwordx4 v[226:229], v[38:39], off
.Lat_norope:
	s_or_b64 exec, exec, s[0:1]
	s_mul_hi_i32 s0, s8, 0x2aaaaaab
	v_add_u32_e32 v37, s11, v145
	s_lshr_b32 s1, s0, 31
	s_lshr_b32 s0, s0, 5
	v_lshlrev_b32_e32 v37, s4, v37
	s_add_i32 s1, s0, s1
	v_add_u32_e32 v37, s5, v37
	s_bfe_u32 s10, s8, 0x20004
	v_lshl_add_u32 v124, s1, 11, v37
	s_lshl_b32 s0, s9, 9
	s_lshl_b32 s6, s10, 7
	v_ashrrev_i32_e32 v125, 31, v124
	v_readlane_b32 s98, v254, 20
	s_or_b32 s0, s0, s6
	v_lshlrev_b64 v[38:39], 12, v[124:125]
	v_readlane_b32 s99, v254, 21
	s_ashr_i32 s1, s0, 31
	v_mov_b32_e32 v121, v36
	v_lshl_add_u64 v[38:39], s[98:99], 0, v[38:39]
	v_lshl_add_u64 v[126:127], s[0:1], 1, v[38:39]
	v_lshlrev_b32_e32 v68, 4, v37
	v_mov_b32_e32 v69, v36
	v_lshl_add_u64 v[38:39], v[126:127], 0, v[120:121]
	v_lshlrev_b64 v[68:69], 2, v[68:69]
	global_load_dwordx4 v[108:111], v[38:39], off
	v_lshl_add_u64 v[70:71], v[118:119], 0, v[68:69]
	v_lshl_add_u64 v[68:69], v[116:117], 0, v[68:69]
	global_load_dwordx4 v[80:83], v[68:69], off offset:16
	global_load_dwordx4 v[88:91], v[68:69], off
	global_load_dwordx4 v[84:87], v[70:71], off offset:16
	global_load_dwordx4 v[92:95], v[70:71], off
	global_load_dwordx4 v[76:79], v[38:39], off offset:64
	global_load_dwordx4 v[72:75], v[38:39], off offset:128
	s_nop 0
	global_load_dwordx4 v[68:71], v[38:39], off offset:192
	s_waitcnt vmcnt(8)
	v_mov_b64_e32 v[102:103], v[6:7]
	v_mov_b64_e32 v[98:99], v[2:3]
	v_mov_b64_e32 v[100:101], v[4:5]
	v_mov_b64_e32 v[96:97], v[0:1]
	s_and_saveexec_b64 s[0:1], vcc
	s_cbranch_execz .LBB0_594
	v_lshlrev_b32_e32 v230, 16, v0
	v_and_b32_e32 v231, 0xffff0000, v0
	v_lshlrev_b32_e32 v232, 16, v4
	v_and_b32_e32 v233, 0xffff0000, v4
	v_pk_mul_f32 v[38:39], v[226:227], v[230:231]
	v_pk_mul_f32 v[226:227], v[226:227], v[232:233]
	v_pk_fma_f32 v[38:39], v[218:219], v[232:233], v[38:39]
	v_pk_fma_f32 v[218:219], v[218:219], v[230:231], v[226:227] neg_lo:[0,0,1] neg_hi:[0,0,1]
	v_lshlrev_b32_e32 v226, 16, v1
	v_and_b32_e32 v227, 0xffff0000, v1
	v_lshlrev_b32_e32 v230, 16, v5
	v_and_b32_e32 v231, 0xffff0000, v5
	v_pk_mul_f32 v[232:233], v[228:229], v[226:227]
	v_pk_mul_f32 v[228:229], v[228:229], v[230:231]
	v_pk_fma_f32 v[232:233], v[220:221], v[230:231], v[232:233]
	v_pk_fma_f32 v[220:221], v[220:221], v[226:227], v[228:229] neg_lo:[0,0,1] neg_hi:[0,0,1]
	v_lshlrev_b32_e32 v226, 16, v2
	v_and_b32_e32 v227, 0xffff0000, v2
	v_lshlrev_b32_e32 v228, 16, v6
	v_and_b32_e32 v229, 0xffff0000, v6
	v_pk_mul_f32 v[230:231], v[222:223], v[226:227]
	v_pk_mul_f32 v[222:223], v[222:223], v[228:229]
	v_pk_fma_f32 v[230:231], v[214:215], v[228:229], v[230:231]
	v_pk_fma_f32 v[214:215], v[214:215], v[226:227], v[222:223] neg_lo:[0,0,1] neg_hi:[0,0,1]
	v_lshlrev_b32_e32 v222, 16, v3
	v_and_b32_e32 v223, 0xffff0000, v3
	v_lshlrev_b32_e32 v226, 16, v7
	v_and_b32_e32 v227, 0xffff0000, v7
	v_pk_mul_f32 v[228:229], v[224:225], v[222:223]
	v_pk_mul_f32 v[224:225], v[224:225], v[226:227]
	v_pk_fma_f32 v[228:229], v[216:217], v[226:227], v[228:229]
	v_pk_fma_f32 v[216:217], v[216:217], v[222:223], v[224:225] neg_lo:[0,0,1] neg_hi:[0,0,1]
	v_cvt_pk_bf16_f32 v96, v218, v219
	v_cvt_pk_bf16_f32 v97, v220, v221
	v_cvt_pk_bf16_f32 v98, v214, v215
	v_cvt_pk_bf16_f32 v99, v216, v217
	v_cvt_pk_bf16_f32 v100, v38, v39
	v_cvt_pk_bf16_f32 v101, v232, v233
	v_cvt_pk_bf16_f32 v102, v230, v231
	v_cvt_pk_bf16_f32 v103, v228, v229
